# v11 + FFN-out phases (P+1, P+8) take row panels in reverse order (newest H panels first) for last-level-cache locality
# baseline (speedup 1.0000x reference)
;     __host__ __device__ bool next(int i, Unit& u) const {
;         const int L = i * G + c; if (L >= nwg) return false;
;         const int nig = WGM * nN, gid = L / nig, fm = gid * WGM, gsz = (nM - fm) < WGM ? (nM - fm) : WGM;
;         u.pm = fm + ((L % nig) % gsz); u.pn = (L % nig) / gsz; return true;
; template <class Epi, class Sched, bool ALIGN_EPI = false, bool SP2 = false>
; __device__ __forceinline__ void gemm_phase(PG8_LAS unsigned char* lds, const Gemm g, const Sched& S, const Epi& E) {
;     ...
;     Unit cur, nxt; int ui = 0;
;     if (!S.next(0, cur)) return;
.LBB0_229:
	s_cmp_lt_i32 s52, 3
	s_cselect_b64 s[0:1], -1, 0
	s_and_b64 s[2:3], s[0:1], s[2:3]
	s_andn2_b64 vcc, exec, s[2:3]
	s_cbranch_vccnz .LBB0_268
	s_cmpk_lt_i32 s10, 0x200
	s_cselect_b64 s[2:3], -1, 0
	s_cmpk_gt_i32 s10, 0x1ff
	v_readfirstlane_b32 s4, v201
	s_cbranch_scc1 .LBB0_232
	s_lshr_b32 s11, s95, 28
	s_add_i32 s11, s95, s11
	s_and_b32 s11, s11, 0xfff0
	s_sub_i32 s11, s95, s11
	s_bfe_i32 s20, s11, 0x80000
	v_readlane_b32 s5, v230, 5
	s_bfe_u32 s20, s20, 0x2000d
	s_lshr_b32 s5, s5, 25
	s_add_i32 s20, s11, s20
	s_add_i32 s5, s10, s5
	s_bfe_i32 s21, s20, 0x80000
	s_and_b32 s20, s20, 0xfc
	s_ashr_i32 s5, s5, 7
	s_sub_i32 s11, s11, s20
	s_lshl_b32 s5, s5, 2
	s_sext_i32_i16 s21, s21
	s_sext_i32_i8 s11, s11
	s_add_i32 s82, s5, s11
	s_sub_i32 s82, 15, s82
	s_ashr_i32 s81, s21, 2

;     __host__ __device__ bool next(int i, Unit& u) const {
;         const int L = i * G + c; if (L >= nwg) return false;
;         const int nig = WGM * nN, gid = L / nig, fm = gid * WGM, gsz = (nM - fm) < WGM ? (nM - fm) : WGM;
;         u.pm = fm + ((L % nig) % gsz); u.pn = (L % nig) / gsz; return true;
; template <class Epi, class Sched, bool ALIGN_EPI = false, bool SP2 = false>
; __device__ __forceinline__ void gemm_phase(PG8_LAS unsigned char* lds, const Gemm g, const Sched& S, const Epi& E) {
;     ...
;         const bool has_next = S.next(ui + 1, nxt);
;         const char* nA = has_next ? (const char*)g.A + (size_t)nxt.pm * tstep : cA; const char* nB = has_next ? (const char*)g.Bt + (size_t)nxt.pn * tstep : cB;
.LBB0_238:
	s_add_i32 s62, s62, 1
	s_mul_i32 s4, s62, s94
	s_add_i32 s4, s4, s95
	s_cmp_lt_i32 s4, 64
	s_cselect_b64 s[46:47], -1, 0
	s_cmp_gt_i32 s4, 63
	s_cbranch_scc1 .LBB0_240
	s_ashr_i32 s5, s4, 31
	s_lshr_b32 s5, s5, 28
	s_add_i32 s5, s4, s5
	s_ashr_i32 s50, s5, 4
	s_and_b32 s5, s5, 0xfff0
	s_sub_i32 s4, s4, s5
	s_bfe_i32 s5, s4, 0x80000
	s_bfe_u32 s5, s5, 0x2000d
	s_add_i32 s5, s4, s5
	s_bfe_i32 s51, s5, 0x80000
	s_and_b32 s5, s5, 0xfc
	s_sub_i32 s4, s4, s5
	s_lshl_b32 s50, s50, 2
	s_sext_i32_i16 s51, s51
	s_sext_i32_i8 s4, s4
	s_add_i32 s80, s50, s4
	s_sub_i32 s80, 15, s80
	s_ashr_i32 s79, s51, 2

;     __host__ __device__ bool next(int i, Unit& u) const {
;         const int L = i * G + c; if (L >= nwg) return false;
;         const int nig = WGM * nN, gid = L / nig, fm = gid * WGM, gsz = (nM - fm) < WGM ? (nM - fm) : WGM;
;         u.pm = fm + ((L % nig) % gsz); u.pn = (L % nig) / gsz; return true;
; template <class Epi, class Sched, bool ALIGN_EPI = false, bool SP2 = false>
; __device__ __forceinline__ void gemm_phase(PG8_LAS unsigned char* lds, const Gemm g, const Sched& S, const Epi& E) {
;     ...
;     Unit cur, nxt; int ui = 0;
;     if (!S.next(0, cur)) return;
.LBB0_714:
	s_cmp_lt_i32 s52, 10
	s_cselect_b64 s[0:1], -1, 0
	s_and_b64 s[2:3], s[0:1], s[4:5]
	s_andn2_b64 vcc, exec, s[2:3]
	s_cbranch_vccnz .LBB0_753
	s_cmpk_lt_i32 s10, 0x200
	s_cselect_b64 s[4:5], -1, 0
	s_cmpk_gt_i32 s10, 0x1ff
	v_readfirstlane_b32 s2, v201
	s_cbranch_scc1 .LBB0_717
	s_lshr_b32 s6, s95, 28
	s_add_i32 s6, s95, s6
	s_and_b32 s6, s6, 0xfff0
	s_sub_i32 s6, s95, s6
	s_bfe_i32 s7, s6, 0x80000
	v_readlane_b32 s3, v230, 5
	s_bfe_u32 s7, s7, 0x2000d
	s_lshr_b32 s3, s3, 25
	s_add_i32 s7, s6, s7
	s_add_i32 s3, s10, s3
	s_bfe_i32 s11, s7, 0x80000
	s_and_b32 s7, s7, 0xfc
	s_ashr_i32 s3, s3, 7
	s_sub_i32 s6, s6, s7
	s_lshl_b32 s3, s3, 2
	s_sext_i32_i16 s11, s11
	s_sext_i32_i8 s6, s6
	s_add_i32 s56, s3, s6
	s_sub_i32 s56, 15, s56
	s_ashr_i32 s3, s11, 2

;     __host__ __device__ bool next(int i, Unit& u) const {
;         const int L = i * G + c; if (L >= nwg) return false;
;         const int nig = WGM * nN, gid = L / nig, fm = gid * WGM, gsz = (nM - fm) < WGM ? (nM - fm) : WGM;
;         u.pm = fm + ((L % nig) % gsz); u.pn = (L % nig) / gsz; return true;
; template <class Epi, class Sched, bool ALIGN_EPI = false, bool SP2 = false>
; __device__ __forceinline__ void gemm_phase(PG8_LAS unsigned char* lds, const Gemm g, const Sched& S, const Epi& E) {
;     ...
;         const bool has_next = S.next(ui + 1, nxt);
;         const char* nA = has_next ? (const char*)g.A + (size_t)nxt.pm * tstep : cA; const char* nB = has_next ? (const char*)g.Bt + (size_t)nxt.pn * tstep : cB;
.LBB0_723:
	s_add_i32 s39, s39, 1
	s_mul_i32 s6, s39, s94
	s_add_i32 s6, s6, s95
	s_cmp_lt_i32 s6, 64
	s_cselect_b64 s[72:73], -1, 0
	s_cmp_gt_i32 s6, 63
	s_cbranch_scc1 .LBB0_725
	s_ashr_i32 s2, s6, 31
	s_lshr_b32 s2, s2, 28
	s_add_i32 s2, s6, s2
	s_ashr_i32 s7, s2, 4
	s_and_b32 s2, s2, 0xfff0
	s_sub_i32 s2, s6, s2
	s_bfe_i32 s6, s2, 0x80000
	s_bfe_u32 s6, s6, 0x2000d
	s_add_i32 s6, s2, s6
	s_bfe_i32 s11, s6, 0x80000
	s_and_b32 s6, s6, 0xfc
	s_sub_i32 s2, s2, s6
	s_lshl_b32 s7, s7, 2
	s_sext_i32_i16 s11, s11
	s_sext_i32_i8 s2, s2
	s_add_i32 s2, s7, s2
	s_sub_i32 s2, 15, s2
	s_ashr_i32 s11, s11, 2

;     __host__ __device__ bool next(int i, Unit& u) const {
;         const int L = i * G + c; if (L >= nwg) return false;
;         const int nig = WGM * nN, gid = L / nig, fm = gid * WGM, gsz = (nM - fm) < WGM ? (nM - fm) : WGM;
;         u.pm = fm + ((L % nig) % gsz); u.pn = (L % nig) / gsz; return true;
; template <class Epi, class Sched, bool ALIGN_EPI = false, bool SP2 = false>
; __device__ __forceinline__ void gemm_phase(PG8_LAS unsigned char* lds, const Gemm g, const Sched& S, const Epi& E) {
;     ...
;     Unit cur, nxt; int ui = 0;
;     if (!S.next(0, cur)) return;
.LBB0_862:
	s_cmp_lt_i32 s52, 12
	s_cselect_b64 s[0:1], -1, 0
	s_and_b64 s[2:3], s[0:1], s[4:5]
	s_andn2_b64 vcc, exec, s[2:3]
	s_cbranch_vccnz .LBB0_901
	s_cmpk_lt_i32 s10, 0x200
	s_cselect_b64 s[4:5], -1, 0
	s_cmpk_gt_i32 s10, 0x1ff
	v_readfirstlane_b32 s2, v201
	s_cbranch_scc1 .LBB0_865
	s_lshr_b32 s6, s95, 28
	s_add_i32 s6, s95, s6
	s_and_b32 s6, s6, 0xfff0
	s_sub_i32 s6, s95, s6
	s_bfe_i32 s7, s6, 0x80000
	v_readlane_b32 s3, v230, 5
	s_bfe_u32 s7, s7, 0x2000d
	s_lshr_b32 s3, s3, 25
	s_add_i32 s7, s6, s7
	s_add_i32 s3, s10, s3
	s_bfe_i32 s11, s7, 0x80000
	s_and_b32 s7, s7, 0xfc
	s_ashr_i32 s3, s3, 7
	s_sub_i32 s6, s6, s7
	s_lshl_b32 s3, s3, 2
	s_sext_i32_i16 s11, s11
	s_sext_i32_i8 s6, s6
	s_add_i32 s56, s3, s6
	s_sub_i32 s56, 15, s56
	s_ashr_i32 s11, s11, 2

;     __host__ __device__ bool next(int i, Unit& u) const {
;         const int L = i * G + c; if (L >= nwg) return false;
;         const int nig = WGM * nN, gid = L / nig, fm = gid * WGM, gsz = (nM - fm) < WGM ? (nM - fm) : WGM;
;         u.pm = fm + ((L % nig) % gsz); u.pn = (L % nig) / gsz; return true;
; template <class Epi, class Sched, bool ALIGN_EPI = false, bool SP2 = false>
; __device__ __forceinline__ void gemm_phase(PG8_LAS unsigned char* lds, const Gemm g, const Sched& S, const Epi& E) {
;     ...
;         const bool has_next = S.next(ui + 1, nxt);
;         const char* nA = has_next ? (const char*)g.A + (size_t)nxt.pm * tstep : cA; const char* nB = has_next ? (const char*)g.Bt + (size_t)nxt.pn * tstep : cB;
.LBB0_871:
	s_add_i32 s39, s39, 1
	s_mul_i32 s6, s39, s94
	s_add_i32 s6, s6, s95
	s_cmp_lt_i32 s6, 64
	s_cselect_b64 s[72:73], -1, 0
	s_cmp_gt_i32 s6, 63
	s_cbranch_scc1 .LBB0_873
	s_ashr_i32 s2, s6, 31
	s_lshr_b32 s2, s2, 28
	s_add_i32 s2, s6, s2
	s_ashr_i32 s3, s2, 4
	s_and_b32 s2, s2, 0xfff0
	s_sub_i32 s2, s6, s2
	s_bfe_i32 s6, s2, 0x80000
	s_bfe_u32 s6, s6, 0x2000d
	s_add_i32 s6, s2, s6
	s_bfe_i32 s7, s6, 0x80000
	s_and_b32 s6, s6, 0xfc
	s_sub_i32 s2, s2, s6
	s_lshl_b32 s3, s3, 2
	s_sext_i32_i16 s7, s7
	s_sext_i32_i8 s2, s2
	s_add_i32 s3, s3, s2
	s_sub_i32 s3, 15, s3
	s_ashr_i32 s2, s7, 2

;     __host__ __device__ bool next(int i, Unit& u) const {
;         const int L = i * G + c; if (L >= nwg) return false;
;         const int nig = WGM * nN, gid = L / nig, fm = gid * WGM, gsz = (nM - fm) < WGM ? (nM - fm) : WGM;
;         u.pm = fm + ((L % nig) % gsz); u.pn = (L % nig) / gsz; return true;
; template <class Epi, class Sched, bool ALIGN_EPI = false, bool SP2 = false>
; __device__ __forceinline__ void gemm_phase(PG8_LAS unsigned char* lds, const Gemm g, const Sched& S, const Epi& E) {
;     ...
;     Unit cur, nxt; int ui = 0;
;     if (!S.next(0, cur)) return;
.LBB0_1347:
	s_cmp_lt_i32 s52, 19
	s_cselect_b64 s[0:1], -1, 0
	s_and_b64 s[2:3], s[0:1], s[2:3]
	s_andn2_b64 vcc, exec, s[2:3]
	s_cbranch_vccnz .LBB0_1386
	s_cmpk_lt_i32 s10, 0x200
	s_cselect_b64 s[2:3], -1, 0
	s_cmpk_gt_i32 s10, 0x1ff
	v_readfirstlane_b32 s4, v201
	s_cbranch_scc1 .LBB0_1350
	s_lshr_b32 s6, s95, 28
	s_add_i32 s6, s95, s6
	s_and_b32 s6, s6, 0xfff0
	s_sub_i32 s6, s95, s6
	v_readlane_b32 s5, v230, 5
	s_bfe_i32 s7, s6, 0x80000
	s_lshr_b32 s5, s5, 25
	s_bfe_u32 s7, s7, 0x2000d
	s_add_i32 s10, s10, s5
	s_add_i32 s7, s6, s7
	s_ashr_i32 s5, s10, 7
	s_bfe_i32 s10, s7, 0x80000
	s_and_b32 s7, s7, 0xfc
	s_sub_i32 s6, s6, s7
	s_lshl_b32 s5, s5, 2
	s_sext_i32_i16 s10, s10
	s_sext_i32_i8 s6, s6
	s_add_i32 s69, s5, s6
	s_sub_i32 s69, 15, s69
	s_ashr_i32 s68, s10, 2

;     __host__ __device__ bool next(int i, Unit& u) const {
;         const int L = i * G + c; if (L >= nwg) return false;
;         const int nig = WGM * nN, gid = L / nig, fm = gid * WGM, gsz = (nM - fm) < WGM ? (nM - fm) : WGM;
;         u.pm = fm + ((L % nig) % gsz); u.pn = (L % nig) / gsz; return true;
; template <class Epi, class Sched, bool ALIGN_EPI = false, bool SP2 = false>
; __device__ __forceinline__ void gemm_phase(PG8_LAS unsigned char* lds, const Gemm g, const Sched& S, const Epi& E) {
;     ...
;         const bool has_next = S.next(ui + 1, nxt);
;         const char* nA = has_next ? (const char*)g.A + (size_t)nxt.pm * tstep : cA; const char* nB = has_next ? (const char*)g.Bt + (size_t)nxt.pn * tstep : cB;
.LBB0_1356:
	s_add_i32 s39, s39, 1
	s_mul_i32 s4, s39, s94
	s_add_i32 s4, s4, s95
	s_cmp_lt_i32 s4, 64
	s_cselect_b64 s[16:17], -1, 0
	s_cmp_gt_i32 s4, 63
	s_cbranch_scc1 .LBB0_1358
	s_ashr_i32 s5, s4, 31
	s_lshr_b32 s5, s5, 28
	s_add_i32 s5, s4, s5
	s_ashr_i32 s18, s5, 4
	s_and_b32 s5, s5, 0xfff0
	s_sub_i32 s4, s4, s5
	s_bfe_i32 s5, s4, 0x80000
	s_bfe_u32 s5, s5, 0x2000d
	s_add_i32 s5, s4, s5
	s_bfe_i32 s19, s5, 0x80000
	s_and_b32 s5, s5, 0xfc
	s_sub_i32 s4, s4, s5
	s_lshl_b32 s18, s18, 2
	s_sext_i32_i16 s19, s19
	s_sext_i32_i8 s4, s4
	s_add_i32 s67, s18, s4
	s_sub_i32 s67, 15, s67
	s_ashr_i32 s66, s19, 2
